# attention softmax rescale subtractions packed (v_pk_add_f32 with neg); N0 bias GEMV wave reductions interleaved
# speedup vs baseline: 1.0035x; 1.0035x over previous
.LBB0_496:
	v_max3_f32 v1, v0, v128, v112
	v_cmp_lt_i32_e32 vcc, v228, v222
	v_max3_f32 v1, v1, v129, v113
	v_max3_f32 v1, v1, v130, v114
	v_max3_f32 v1, v1, v131, v115
	v_cndmask_b32_e32 v10, v221, v228, vcc
	v_max3_f32 v1, v1, v132, v116
	v_lshlrev_b32_e32 v243, 2, v10
	v_max3_f32 v1, v1, v133, v117
	v_max3_f32 v1, v1, v134, v118
	v_max3_f32 v1, v1, v135, v119
	v_max3_f32 v1, v1, v136, v120
	v_max3_f32 v1, v1, v137, v121
	v_max3_f32 v1, v1, v138, v122
	v_max3_f32 v1, v1, v139, v123
	v_max3_f32 v1, v1, v140, v124
	v_max3_f32 v1, v1, v141, v125
	v_max3_f32 v1, v1, v142, v126
	v_max3_f32 v1, v1, v143, v127
	ds_bpermute_b32 v10, v243, v1
	s_waitcnt lgkmcnt(0)
	v_max3_f32 v1, v1, v1, v10
	v_cmp_lt_f32_e32 vcc, s33, v1
	s_cbranch_vccz .LBB0_498
	v_exp_f32_e64 v10, -v1
	v_add_f32_e32 v197, v197, v1
	v_pk_add_f32 v[142:143], v[142:143], v[0:1] op_sel:[0,1] op_sel_hi:[1,1] neg_lo:[0,1] neg_hi:[0,1]
	v_pk_add_f32 v[140:141], v[140:141], v[0:1] op_sel:[0,1] op_sel_hi:[1,1] neg_lo:[0,1] neg_hi:[0,1]
	v_pk_add_f32 v[138:139], v[138:139], v[0:1] op_sel:[0,1] op_sel_hi:[1,1] neg_lo:[0,1] neg_hi:[0,1]
	v_pk_add_f32 v[136:137], v[136:137], v[0:1] op_sel:[0,1] op_sel_hi:[1,1] neg_lo:[0,1] neg_hi:[0,1]
	v_pk_add_f32 v[134:135], v[134:135], v[0:1] op_sel:[0,1] op_sel_hi:[1,1] neg_lo:[0,1] neg_hi:[0,1]
	v_pk_add_f32 v[132:133], v[132:133], v[0:1] op_sel:[0,1] op_sel_hi:[1,1] neg_lo:[0,1] neg_hi:[0,1]
	v_pk_add_f32 v[130:131], v[130:131], v[0:1] op_sel:[0,1] op_sel_hi:[1,1] neg_lo:[0,1] neg_hi:[0,1]
	v_pk_add_f32 v[128:129], v[128:129], v[0:1] op_sel:[0,1] op_sel_hi:[1,1] neg_lo:[0,1] neg_hi:[0,1]
	v_pk_mul_f32 v[78:79], v[78:79], v[10:11] op_sel_hi:[1,0]
	v_pk_mul_f32 v[76:77], v[76:77], v[10:11] op_sel_hi:[1,0]
	v_pk_mul_f32 v[74:75], v[74:75], v[10:11] op_sel_hi:[1,0]
	v_pk_mul_f32 v[72:73], v[72:73], v[10:11] op_sel_hi:[1,0]
	v_pk_mul_f32 v[70:71], v[70:71], v[10:11] op_sel_hi:[1,0]
	v_pk_mul_f32 v[68:69], v[68:69], v[10:11] op_sel_hi:[1,0]
	v_pk_mul_f32 v[66:67], v[66:67], v[10:11] op_sel_hi:[1,0]
	v_pk_mul_f32 v[64:65], v[64:65], v[10:11] op_sel_hi:[1,0]
	v_pk_mul_f32 v[62:63], v[62:63], v[10:11] op_sel_hi:[1,0]
	v_pk_mul_f32 v[60:61], v[60:61], v[10:11] op_sel_hi:[1,0]
	v_pk_mul_f32 v[58:59], v[58:59], v[10:11] op_sel_hi:[1,0]
	v_pk_mul_f32 v[56:57], v[56:57], v[10:11] op_sel_hi:[1,0]
	v_pk_mul_f32 v[54:55], v[54:55], v[10:11] op_sel_hi:[1,0]
	v_pk_mul_f32 v[52:53], v[52:53], v[10:11] op_sel_hi:[1,0]
	v_pk_mul_f32 v[50:51], v[50:51], v[10:11] op_sel_hi:[1,0]
	v_pk_mul_f32 v[48:49], v[48:49], v[10:11] op_sel_hi:[1,0]
	v_mul_f32_e32 v241, v241, v10
	v_pk_add_f32 v[126:127], v[126:127], v[0:1] op_sel:[0,1] op_sel_hi:[1,1] neg_lo:[0,1] neg_hi:[0,1]
	v_pk_add_f32 v[124:125], v[124:125], v[0:1] op_sel:[0,1] op_sel_hi:[1,1] neg_lo:[0,1] neg_hi:[0,1]
	v_pk_add_f32 v[122:123], v[122:123], v[0:1] op_sel:[0,1] op_sel_hi:[1,1] neg_lo:[0,1] neg_hi:[0,1]
	v_pk_add_f32 v[120:121], v[120:121], v[0:1] op_sel:[0,1] op_sel_hi:[1,1] neg_lo:[0,1] neg_hi:[0,1]
	v_pk_add_f32 v[118:119], v[118:119], v[0:1] op_sel:[0,1] op_sel_hi:[1,1] neg_lo:[0,1] neg_hi:[0,1]
	v_pk_add_f32 v[116:117], v[116:117], v[0:1] op_sel:[0,1] op_sel_hi:[1,1] neg_lo:[0,1] neg_hi:[0,1]
	v_pk_add_f32 v[114:115], v[114:115], v[0:1] op_sel:[0,1] op_sel_hi:[1,1] neg_lo:[0,1] neg_hi:[0,1]
	v_pk_add_f32 v[112:113], v[112:113], v[0:1] op_sel:[0,1] op_sel_hi:[1,1] neg_lo:[0,1] neg_hi:[0,1]

.LBB0_500:
	v_max3_f32 v127, v0, v96, v80
	v_max3_f32 v127, v127, v97, v81
	v_max3_f32 v127, v127, v98, v82
	v_max3_f32 v127, v127, v99, v83
	v_max3_f32 v127, v127, v100, v84
	v_max3_f32 v127, v127, v101, v85
	v_max3_f32 v127, v127, v102, v86
	v_max3_f32 v127, v127, v103, v87
	v_max3_f32 v127, v127, v104, v88
	v_max3_f32 v127, v127, v105, v89
	v_max3_f32 v127, v127, v106, v90
	v_max3_f32 v127, v127, v107, v91
	v_max3_f32 v127, v127, v108, v92
	v_max3_f32 v127, v127, v109, v93
	v_max3_f32 v127, v127, v110, v94
	v_max3_f32 v127, v127, v111, v95
	ds_bpermute_b32 v136, v243, v127
	s_waitcnt lgkmcnt(0)
	v_max3_f32 v127, v127, v127, v136
	v_cmp_lt_f32_e32 vcc, s33, v127
	s_cbranch_vccz .LBB0_502
	v_exp_f32_e64 v136, -v127
	v_add_f32_e32 v239, v239, v127
	v_pk_add_f32 v[110:111], v[110:111], v[126:127] op_sel:[0,1] op_sel_hi:[1,1] neg_lo:[0,1] neg_hi:[0,1]
	v_pk_add_f32 v[108:109], v[108:109], v[126:127] op_sel:[0,1] op_sel_hi:[1,1] neg_lo:[0,1] neg_hi:[0,1]
	v_pk_add_f32 v[106:107], v[106:107], v[126:127] op_sel:[0,1] op_sel_hi:[1,1] neg_lo:[0,1] neg_hi:[0,1]
	v_pk_add_f32 v[104:105], v[104:105], v[126:127] op_sel:[0,1] op_sel_hi:[1,1] neg_lo:[0,1] neg_hi:[0,1]
	v_pk_add_f32 v[102:103], v[102:103], v[126:127] op_sel:[0,1] op_sel_hi:[1,1] neg_lo:[0,1] neg_hi:[0,1]
	v_pk_add_f32 v[100:101], v[100:101], v[126:127] op_sel:[0,1] op_sel_hi:[1,1] neg_lo:[0,1] neg_hi:[0,1]
	v_pk_add_f32 v[98:99], v[98:99], v[126:127] op_sel:[0,1] op_sel_hi:[1,1] neg_lo:[0,1] neg_hi:[0,1]
	v_pk_add_f32 v[96:97], v[96:97], v[126:127] op_sel:[0,1] op_sel_hi:[1,1] neg_lo:[0,1] neg_hi:[0,1]
	v_pk_mul_f32 v[46:47], v[46:47], v[136:137] op_sel_hi:[1,0]
	v_pk_mul_f32 v[44:45], v[44:45], v[136:137] op_sel_hi:[1,0]
	v_pk_mul_f32 v[42:43], v[42:43], v[136:137] op_sel_hi:[1,0]
	v_pk_mul_f32 v[40:41], v[40:41], v[136:137] op_sel_hi:[1,0]
	v_pk_mul_f32 v[38:39], v[38:39], v[136:137] op_sel_hi:[1,0]
	v_pk_mul_f32 v[36:37], v[36:37], v[136:137] op_sel_hi:[1,0]
	v_pk_mul_f32 v[34:35], v[34:35], v[136:137] op_sel_hi:[1,0]
	v_pk_mul_f32 v[32:33], v[32:33], v[136:137] op_sel_hi:[1,0]
	v_pk_mul_f32 v[30:31], v[30:31], v[136:137] op_sel_hi:[1,0]
	v_pk_mul_f32 v[28:29], v[28:29], v[136:137] op_sel_hi:[1,0]
	v_pk_mul_f32 v[26:27], v[26:27], v[136:137] op_sel_hi:[1,0]
	v_pk_mul_f32 v[24:25], v[24:25], v[136:137] op_sel_hi:[1,0]
	v_pk_mul_f32 v[22:23], v[22:23], v[136:137] op_sel_hi:[1,0]
	v_pk_mul_f32 v[20:21], v[20:21], v[136:137] op_sel_hi:[1,0]
	v_pk_mul_f32 v[18:19], v[18:19], v[136:137] op_sel_hi:[1,0]
	v_pk_mul_f32 v[16:17], v[16:17], v[136:137] op_sel_hi:[1,0]
	v_mul_f32_e32 v238, v238, v136
	v_pk_add_f32 v[94:95], v[94:95], v[126:127] op_sel:[0,1] op_sel_hi:[1,1] neg_lo:[0,1] neg_hi:[0,1]
	v_pk_add_f32 v[92:93], v[92:93], v[126:127] op_sel:[0,1] op_sel_hi:[1,1] neg_lo:[0,1] neg_hi:[0,1]
	v_pk_add_f32 v[90:91], v[90:91], v[126:127] op_sel:[0,1] op_sel_hi:[1,1] neg_lo:[0,1] neg_hi:[0,1]
	v_pk_add_f32 v[88:89], v[88:89], v[126:127] op_sel:[0,1] op_sel_hi:[1,1] neg_lo:[0,1] neg_hi:[0,1]
	v_pk_add_f32 v[86:87], v[86:87], v[126:127] op_sel:[0,1] op_sel_hi:[1,1] neg_lo:[0,1] neg_hi:[0,1]
	v_pk_add_f32 v[84:85], v[84:85], v[126:127] op_sel:[0,1] op_sel_hi:[1,1] neg_lo:[0,1] neg_hi:[0,1]
	v_pk_add_f32 v[82:83], v[82:83], v[126:127] op_sel:[0,1] op_sel_hi:[1,1] neg_lo:[0,1] neg_hi:[0,1]
	v_pk_add_f32 v[80:81], v[80:81], v[126:127] op_sel:[0,1] op_sel_hi:[1,1] neg_lo:[0,1] neg_hi:[0,1]
